# cache policy: final_norm residual-stream reads marked nt (read once)
# speedup vs baseline: 1.0053x; 1.0053x over previous
.LBB7_1426:
	s_cmp_lt_i32 s87, 31
	s_cselect_b64 s[0:1], -1, 0
	s_cmp_gt_i32 s89, 30
	s_cselect_b64 s[2:3], -1, 0
	s_and_b64 s[0:1], s[0:1], s[2:3]
	s_and_b64 vcc, exec, s[0:1]
	v_readlane_b32 s12, v251, 8
	v_readlane_b32 s13, v251, 9
	s_cbranch_vccz .LBB7_1432
	v_readlane_b32 s0, v251, 0
	v_readlane_b32 s1, v251, 1
	s_cmpk_gt_i32 s12, 0x7fff
	v_writelane_b32 v251, s0, 0
	s_nop 1
	v_writelane_b32 v251, s1, 1
	s_cbranch_scc1 .LBB7_1432
	v_readlane_b32 s0, v251, 0
	v_readlane_b32 s1, v251, 1
	s_load_dwordx4 s[4:7], s[0:1], 0x110
	s_load_dwordx2 s[2:3], s[0:1], 0x120
	s_waitcnt vmcnt(0)
	v_lshlrev_b32_e32 v20, 5, v201
	v_and_b32_e32 v16, 64, v163
	v_add_u32_e32 v16, 64, v16
	s_waitcnt lgkmcnt(0)
	global_load_dwordx4 v[0:3], v20, s[4:5] offset:16
	global_load_dwordx4 v[4:7], v20, s[4:5]
	global_load_dwordx4 v[8:11], v20, s[4:5] offset:2064
	global_load_dwordx4 v[12:15], v20, s[4:5] offset:2048
	v_xor_b32_e32 v17, 1, v163
	v_cmp_lt_i32_e32 vcc, v17, v16
	s_ashr_i32 s13, s12, 31
	s_lshl_b64 s[0:1], s[12:13], 6
	v_cndmask_b32_e32 v17, v163, v17, vcc
	v_lshlrev_b32_e32 v22, 2, v17
	v_xor_b32_e32 v17, 2, v163
	v_cmp_lt_i32_e32 vcc, v17, v16
	s_add_u32 s0, s2, s0
	v_readlane_b32 s14, v251, 6
	v_cndmask_b32_e32 v17, v163, v17, vcc
	v_lshlrev_b32_e32 v23, 2, v17
	v_xor_b32_e32 v17, 4, v163
	v_cmp_lt_i32_e32 vcc, v17, v16
	v_lshlrev_b32_e32 v28, 2, v201
	v_mov_b32_e32 v29, 0
	v_cndmask_b32_e32 v17, v163, v17, vcc
	v_lshlrev_b32_e32 v24, 2, v17
	v_xor_b32_e32 v17, 8, v163
	v_cmp_lt_i32_e32 vcc, v17, v16
	s_addc_u32 s1, s3, s1
	v_readlane_b32 s15, v251, 7
	v_cndmask_b32_e32 v17, v163, v17, vcc
	v_lshlrev_b32_e32 v25, 2, v17
	v_xor_b32_e32 v17, 16, v163
	v_cmp_lt_i32_e32 vcc, v17, v16
	s_ashr_i32 s15, s14, 31
	s_lshl_b64 s[4:5], s[12:13], 11
	v_cndmask_b32_e32 v17, v163, v17, vcc
	v_lshlrev_b32_e32 v26, 2, v17
	v_xor_b32_e32 v17, 32, v163
	v_cmp_lt_i32_e32 vcc, v17, v16
	v_mov_b32_e32 v21, v29
	v_readlane_b32 s16, v251, 4
	v_cndmask_b32_e32 v16, v163, v17, vcc
	v_lshlrev_b32_e32 v27, 2, v16
	v_lshl_add_u64 v[16:17], s[0:1], 0, v[28:29]
	s_mov_b64 s[0:1], 0x1ce80000
	v_lshl_add_u64 v[16:17], v[16:17], 0, s[0:1]
	s_lshl_b64 s[0:1], s[14:15], 6
	s_add_u32 s2, s2, s4
	v_lshlrev_b32_e32 v28, 4, v201
	s_addc_u32 s3, s3, s5
	v_lshl_add_u64 v[18:19], s[2:3], 0, v[28:29]
	s_mov_b64 s[2:3], 0xa380400
	v_lshl_add_u64 v[18:19], v[18:19], 0, s[2:3]
	s_lshl_b64 s[2:3], s[14:15], 11
	s_lshl_b64 s[4:5], s[12:13], 12
	s_add_u32 s4, s6, s4
	s_addc_u32 s5, s7, s5
	v_lshl_add_u64 v[20:21], s[4:5], 0, v[20:21]
	s_lshl_b64 s[4:5], s[14:15], 12
	v_mov_b32_e32 v28, 0x358637bd
	s_mov_b32 s8, 0x800000
	v_readlane_b32 s17, v251, 5
	v_mov_b32_e32 v29, 0
	s_and_saveexec_b64 s[6:7], s[16:17]
	global_load_dword v29, v[16:17], off
	s_or_b64 exec, exec, s[6:7]
	global_load_dwordx4 v[30:33], v[18:19], off offset:-1024 nt
	global_load_dwordx4 v[34:37], v[18:19], off nt
	s_waitcnt vmcnt(0)
	s_branch .Lfn_body

.Lfn_body:
	v_mov_b32_e32 v80, v29
	v_mov_b64_e32 v[56:57], v[30:31]
	v_mov_b64_e32 v[58:59], v[32:33]
	v_mov_b64_e32 v[60:61], v[34:35]
	v_mov_b64_e32 v[62:63], v[36:37]
	s_add_i32 s12, s12, s14
	v_lshl_add_u64 v[16:17], v[16:17], 0, s[0:1]
	v_lshl_add_u64 v[18:19], v[18:19], 0, s[2:3]
	s_cmp_lt_i32 s12, 0x8000
	s_cbranch_scc0 .Lfn_nopf
	v_mov_b32_e32 v29, 0
	s_and_saveexec_b64 s[6:7], s[16:17]
	global_load_dword v29, v[16:17], off
	s_or_b64 exec, exec, s[6:7]
	global_load_dwordx4 v[30:33], v[18:19], off offset:-1024 nt
	global_load_dwordx4 v[34:37], v[18:19], off nt
